# weight conversion split tuned: items >=1876 (one per wave) done by workgroups >=128 ahead of their FFN1-up tiles, the rest before the sync
# speedup vs baseline: 1.0172x; 1.0074x over previous
; #define LAS __attribute__((address_space(3)))
; __device__ __forceinline__ void conv_item(const float* __restrict__ W, const float* __restrict__ g, int K, int NS, int NP, bf16_t* __restrict__ dst, int ldd, int koff, int row_off, int ilv,
;                                           LAS float* scr, int item, int lane) {
;     ...
;     for (int j = 0; j < 16; ++j) {
;         const int idx = j * 64 + lane, nl = idx >> 3, q = idx & 7, nn = n0 + nl;
;         const u32x4 o = *(const LAS u32x4*)(tile + nl * 128 + ((q ^ ((nl >> 1) & 7)) << 4));
.LBB0_1764:
	s_lshr_b32 s0, s1, 1
	v_writelane_b32 v252, s0, 25
	s_and_b32 s0, s1, 1
	s_cmp_eq_u32 s0, 0
	s_cselect_b64 s[12:13], -1, 0
	s_cmp_eq_u32 s0, 1
	s_cselect_b64 s[2:3], -1, 0
	s_cmp_eq_u32 s1, 0
	s_cselect_b64 s[6:7], -1, 0
	v_writelane_b32 v252, s1, 26
	s_and_b64 vcc, exec, s[6:7]
	s_cbranch_vccnz .LBB0_3143
	s_mov_b64 s[0:1], s[88:89]
	v_mov_b32_e32 v1, v220
	s_movk_i32 s11, 0x70
	v_and_b32_e32 v4, 63, v1
	v_readfirstlane_b32 s4, v1
	s_waitcnt vmcnt(9)
	v_and_b32_e32 v70, 7, v1
	v_lshlrev_b32_e32 v5, 4, v4
	v_lshlrev_b32_e32 v2, 3, v1
	v_bfe_u32 v72, v1, 3, 3
	v_or_b32_e32 v1, 64, v4
	v_lshrrev_b32_e32 v75, 3, v1
	v_bitop3_b32 v77, v1, s11, v5 bitop3:0x48
	v_or_b32_e32 v1, 0xc0, v4
	v_lshrrev_b32_e32 v80, 3, v1
	v_bitop3_b32 v82, v1, s11, v5 bitop3:0x48
	v_or_b32_e32 v1, 0x140, v4
	v_lshrrev_b32_e32 v85, 3, v1
	v_bitop3_b32 v87, v1, s11, v5 bitop3:0x48
	v_or_b32_e32 v1, 0x1c0, v4
	s_waitcnt vmcnt(8)
	v_lshrrev_b32_e32 v90, 3, v1
	v_bitop3_b32 v92, v1, s11, v5 bitop3:0x48
	v_or_b32_e32 v1, 0x240, v4
	v_lshrrev_b32_e32 v95, 3, v1
	v_bitop3_b32 v97, v1, s11, v5 bitop3:0x48
	v_or_b32_e32 v1, 0x2c0, v4
	s_ashr_i32 s4, s4, 6
	v_readlane_b32 s5, v252, 0
	v_lshrrev_b32_e32 v100, 3, v1
	v_bitop3_b32 v102, v1, s11, v5 bitop3:0x48
	v_or_b32_e32 v1, 0x340, v4
	s_add_i32 s48, s4, s5
	s_lshl_b32 s4, s4, 14
	v_lshrrev_b32_e32 v105, 3, v1
	v_bitop3_b32 v107, v1, s11, v5 bitop3:0x48
	v_or_b32_e32 v1, 0x3c0, v4
	v_readlane_b32 s26, v252, 25
	s_add_i32 s10, s4, 0
	v_readlane_b32 s14, v252, 26
	v_or_b32_e32 v78, 16, v72
	v_or_b32_e32 v83, 32, v72
	v_or_b32_e32 v88, 48, v72
	v_or_b32_e32 v93, 64, v72
	v_or_b32_e32 v98, 0x50, v72
	v_or_b32_e32 v103, 0x60, v72
	v_or_b32_e32 v108, 0x70, v72
	v_lshrrev_b32_e32 v110, 3, v1
	s_mul_i32 s16, s26, 0x1b2000
	s_mov_b32 s17, s68
	s_lshl_b32 s18, s26, 20
	s_mov_b32 s19, s68
	s_mul_i32 s20, s26, 0x2a8000
	s_mov_b32 s21, s68
	s_mul_i32 s22, s26, 0x30000
	s_mov_b32 s23, s68
	s_lshl_b32 s24, s26, 17
	s_mov_b32 s25, s68
	s_mul_i32 s26, s26, 0xc0000
	s_mov_b32 s27, s68
	s_mul_i32 s4, s14, 0x580000
	s_mov_b32 s5, s68
	s_lshl_b32 s8, s14, 10
	s_mov_b32 s9, s68
	s_waitcnt lgkmcnt(0)
	v_lshlrev_b32_e32 v3, 1, v4
	v_lshl_add_u32 v71, v4, 8, s10
	v_and_b32_e32 v2, 56, v2
	v_bitop3_b32 v73, v5, s11, v4 bitop3:0x48
	v_lshl_add_u32 v74, v72, 7, s10
	v_lshl_add_u32 v76, v75, 7, s10
	v_lshl_add_u32 v79, v78, 7, s10
	v_lshl_add_u32 v81, v80, 7, s10
	v_lshl_add_u32 v84, v83, 7, s10
	v_lshl_add_u32 v86, v85, 7, s10
	v_lshl_add_u32 v89, v88, 7, s10
	v_lshl_add_u32 v91, v90, 7, s10
	v_lshl_add_u32 v94, v93, 7, s10
	v_lshl_add_u32 v96, v95, 7, s10
	v_lshl_add_u32 v99, v98, 7, s10
	v_lshl_add_u32 v101, v100, 7, s10
	v_lshl_add_u32 v104, v103, 7, s10
	v_lshl_add_u32 v106, v105, 7, s10
	v_lshl_add_u32 v109, v108, 7, s10
	v_lshl_add_u32 v111, v110, 7, s10
	v_bitop3_b32 v112, v1, s11, v5 bitop3:0x48
	s_mul_i32 s10, s14, 0x2c0000
	s_mov_b32 s11, s68
	s_lshl_b32 s14, s14, 20
	s_mov_b32 s15, s68
	s_lshl_b64 s[16:17], s[16:17], 2
	s_lshl_b64 s[18:19], s[18:19], 2
	s_lshl_b64 s[20:21], s[20:21], 2
	s_lshl_b64 s[22:23], s[22:23], 2
	s_lshl_b64 s[24:25], s[24:25], 2
	s_lshl_b64 s[26:27], s[26:27], 2
	v_readlane_b32 s28, v254, 40
	s_nop 1
	s_cmp_eq_u32 s28, 0
	s_cbranch_scc1 .Lmy_conv_m0
	s_addk_i32 s48, 0x354

.LBB0_1767:
	v_readlane_b32 s28, v254, 40
	s_nop 1
	s_cmp_eq_u32 s28, 0
	s_cbranch_scc0 .Lmy_conv_disp
	s_cmpk_ge_i32 s48, 1876
	s_cbranch_scc1 .LBB0_3090
